# EpiResid epilogues (out-proj + down-proj GEMMs): 16B loads/stores via v_permlane16_swap pairing of n=0/n=1 pieces (halves VMEM instruction count), same f32 add + RNE pack
# speedup vs baseline: 1.0054x; 1.0049x over previous
; __device__ __forceinline__ unsigned pk2_(float lo, float hi) { f32x2_t v = {lo, hi}; bf16x2_t b = __builtin_convertvector(v, bf16x2_t); return __builtin_bit_cast(unsigned, b); }
;     __device__ __forceinline__ void operator()(const f32x4 (&acc)[2][2][4][2], const Unit& u, int wr, int wc, int fr, int fq) const {
;         typedef unsigned u32x2_ __attribute__((ext_vector_type(2)));
;         const int col0 = u.pn * BM + wc * 32 + 4 * fq;
; #pragma unroll
;         for (int ai = 0; ai < 2; ++ai) {
;             u32x2_ v[4][2][2];
; #pragma unroll
;             for (int m = 0; m < 4; ++m) { const bf16_t* rowp = H + (size_t)(u.pm * BM + wr * 64 + fr + ai * HALF + m * 16) * 2048 + col0;
; #pragma unroll
;                 for (int bj = 0; bj < 2; ++bj)
; #pragma unroll
;                     for (int n = 0; n < 2; ++n) v[m][bj][n] = *(const u32x2_*)(rowp + bj * HALF + n * 16); }
; #pragma unroll
;             for (int m = 0; m < 4; ++m) { bf16_t* rowp = H + (size_t)(u.pm * BM + wr * 64 + fr + ai * HALF + m * 16) * 2048 + col0;
; #pragma unroll
;                 for (int bj = 0; bj < 2; ++bj)
; #pragma unroll
;                     for (int n = 0; n < 2; ++n) { const f32x4 a = acc[ai][bj][m][n]; const u32x2_ o = v[m][bj][n];
;                         u32x2_ w; w.x = pk2_(bflo(o.x) + a[0], bfhi(o.x) + a[1]); w.y = pk2_(bflo(o.y) + a[2], bfhi(o.y) + a[3]); *(u32x2_*)(rowp + bj * HALF + n * 16) = w; } }
;             asm volatile("" ::: "memory");
;         }
;     }
.LBB0_1375:
	v_and_b32_e32 v142, 16, v213
	v_lshrrev_b32_e32 v142, 2, v142
	v_mul_u32_u24_e32 v142, 3, v142
	v_add_u32_e32 v143, v179, v142
	v_lshl_or_b32 v143, s22, 8, v143
	v_lshl_add_u32 v176, s28, 8, v17
	v_lshlrev_b32_e32 v176, 12, v176
	v_lshl_add_u32 v176, v143, 1, v176
	v_mov_b32_e32 v193, v176
	global_load_dwordx4 v[144:147], v176, s[42:43]
	global_load_dwordx4 v[148:151], v176, s[42:43] offset:256
	v_add_u32_e32 v176, 0x10000, v176
	global_load_dwordx4 v[152:155], v176, s[42:43]
	global_load_dwordx4 v[156:159], v176, s[42:43] offset:256
	v_add_u32_e32 v176, 0x10000, v176
	global_load_dwordx4 v[160:163], v176, s[42:43]
	global_load_dwordx4 v[164:167], v176, s[42:43] offset:256
	v_add_u32_e32 v176, 0x10000, v176
	global_load_dwordx4 v[168:171], v176, s[42:43]
	global_load_dwordx4 v[172:175], v176, s[42:43] offset:256
	v_add_u32_e32 v176, 0x50000, v176
	s_waitcnt vmcnt(7)
	v_permlane16_swap_b32_e32 v144, v146
	v_permlane16_swap_b32_e32 v145, v147
	v_lshlrev_b32_e32 v177, 16, v144
	v_and_b32_e32 v182, 0xffff0000, v144
	v_lshlrev_b32_e32 v183, 16, v145
	v_and_b32_e32 v192, 0xffff0000, v145
	v_add_f32_e32 v126, v126, v177
	v_add_f32_e32 v127, v127, v182
	v_add_f32_e32 v128, v128, v183
	v_add_f32_e32 v129, v129, v192
	v_lshlrev_b32_e32 v177, 16, v146
	v_and_b32_e32 v182, 0xffff0000, v146
	v_lshlrev_b32_e32 v183, 16, v147
	v_and_b32_e32 v192, 0xffff0000, v147
	v_add_f32_e32 v122, v122, v177
	v_add_f32_e32 v123, v123, v182
	v_add_f32_e32 v124, v124, v183
	v_add_f32_e32 v125, v125, v192
	v_cvt_pk_bf16_f32 v144, v126, v127
	v_cvt_pk_bf16_f32 v145, v128, v129
	v_cvt_pk_bf16_f32 v146, v122, v123
	v_cvt_pk_bf16_f32 v147, v124, v125
	s_nop 1
	v_permlane16_swap_b32_e32 v144, v146
	v_permlane16_swap_b32_e32 v145, v147
	global_store_dwordx4 v193, v[144:147], s[42:43]
	s_waitcnt vmcnt(7)
	v_permlane16_swap_b32_e32 v148, v150
	v_permlane16_swap_b32_e32 v149, v151
	v_lshlrev_b32_e32 v177, 16, v148
	v_and_b32_e32 v182, 0xffff0000, v148
	v_lshlrev_b32_e32 v183, 16, v149
	v_and_b32_e32 v192, 0xffff0000, v149
	v_add_f32_e32 v118, v118, v177
	v_add_f32_e32 v119, v119, v182
	v_add_f32_e32 v120, v120, v183
	v_add_f32_e32 v121, v121, v192
	v_lshlrev_b32_e32 v177, 16, v150
	v_and_b32_e32 v182, 0xffff0000, v150
	v_lshlrev_b32_e32 v183, 16, v151
	v_and_b32_e32 v192, 0xffff0000, v151
	v_add_f32_e32 v114, v114, v177
	v_add_f32_e32 v115, v115, v182
	v_add_f32_e32 v116, v116, v183
	v_add_f32_e32 v117, v117, v192
	v_cvt_pk_bf16_f32 v148, v118, v119
	v_cvt_pk_bf16_f32 v149, v120, v121
	v_cvt_pk_bf16_f32 v150, v114, v115
	v_cvt_pk_bf16_f32 v151, v116, v117
	s_nop 1
	v_permlane16_swap_b32_e32 v148, v150
	v_permlane16_swap_b32_e32 v149, v151
	global_store_dwordx4 v193, v[148:151], s[42:43] offset:256
	v_add_u32_e32 v193, 0x10000, v193
	s_waitcnt vmcnt(7)
	v_permlane16_swap_b32_e32 v152, v154
	v_permlane16_swap_b32_e32 v153, v155
	v_lshlrev_b32_e32 v177, 16, v152
	v_and_b32_e32 v182, 0xffff0000, v152
	v_lshlrev_b32_e32 v183, 16, v153
	v_and_b32_e32 v192, 0xffff0000, v153
	v_add_f32_e32 v110, v110, v177
	v_add_f32_e32 v111, v111, v182
	v_add_f32_e32 v112, v112, v183
	v_add_f32_e32 v113, v113, v192
	v_lshlrev_b32_e32 v177, 16, v154
	v_and_b32_e32 v182, 0xffff0000, v154
	v_lshlrev_b32_e32 v183, 16, v155
	v_and_b32_e32 v192, 0xffff0000, v155
	v_add_f32_e32 v106, v106, v177
	v_add_f32_e32 v107, v107, v182
	v_add_f32_e32 v108, v108, v183
	v_add_f32_e32 v109, v109, v192
	v_cvt_pk_bf16_f32 v152, v110, v111
	v_cvt_pk_bf16_f32 v153, v112, v113
	v_cvt_pk_bf16_f32 v154, v106, v107
	v_cvt_pk_bf16_f32 v155, v108, v109
	s_nop 1
	v_permlane16_swap_b32_e32 v152, v154
	v_permlane16_swap_b32_e32 v153, v155
	global_store_dwordx4 v193, v[152:155], s[42:43]
	s_waitcnt vmcnt(7)
	v_permlane16_swap_b32_e32 v156, v158
	v_permlane16_swap_b32_e32 v157, v159
	v_lshlrev_b32_e32 v177, 16, v156
	v_and_b32_e32 v182, 0xffff0000, v156
	v_lshlrev_b32_e32 v183, 16, v157
	v_and_b32_e32 v192, 0xffff0000, v157
	v_add_f32_e32 v102, v102, v177
	v_add_f32_e32 v103, v103, v182
	v_add_f32_e32 v104, v104, v183
	v_add_f32_e32 v105, v105, v192
	v_lshlrev_b32_e32 v177, 16, v158
	v_and_b32_e32 v182, 0xffff0000, v158
	v_lshlrev_b32_e32 v183, 16, v159
	v_and_b32_e32 v192, 0xffff0000, v159
	v_add_f32_e32 v94, v94, v177
	v_add_f32_e32 v95, v95, v182
	v_add_f32_e32 v96, v96, v183
	v_add_f32_e32 v97, v97, v192
	v_cvt_pk_bf16_f32 v156, v102, v103
	v_cvt_pk_bf16_f32 v157, v104, v105
	v_cvt_pk_bf16_f32 v158, v94, v95
	v_cvt_pk_bf16_f32 v159, v96, v97
	s_nop 1
	v_permlane16_swap_b32_e32 v156, v158
	v_permlane16_swap_b32_e32 v157, v159
	global_store_dwordx4 v193, v[156:159], s[42:43] offset:256
	v_add_u32_e32 v193, 0x10000, v193
	s_waitcnt vmcnt(7)
	v_permlane16_swap_b32_e32 v160, v162
	v_permlane16_swap_b32_e32 v161, v163
	v_lshlrev_b32_e32 v177, 16, v160
	v_and_b32_e32 v182, 0xffff0000, v160
	v_lshlrev_b32_e32 v183, 16, v161
	v_and_b32_e32 v192, 0xffff0000, v161
	v_add_f32_e32 v98, v98, v177
	v_add_f32_e32 v99, v99, v182
	v_add_f32_e32 v100, v100, v183
	v_add_f32_e32 v101, v101, v192
	v_lshlrev_b32_e32 v177, 16, v162
	v_and_b32_e32 v182, 0xffff0000, v162
	v_lshlrev_b32_e32 v183, 16, v163
	v_and_b32_e32 v192, 0xffff0000, v163
	v_add_f32_e32 v90, v90, v177
	v_add_f32_e32 v91, v91, v182
	v_add_f32_e32 v92, v92, v183
	v_add_f32_e32 v93, v93, v192
	v_cvt_pk_bf16_f32 v160, v98, v99
	v_cvt_pk_bf16_f32 v161, v100, v101
	v_cvt_pk_bf16_f32 v162, v90, v91
	v_cvt_pk_bf16_f32 v163, v92, v93
	s_nop 1
	v_permlane16_swap_b32_e32 v160, v162
	v_permlane16_swap_b32_e32 v161, v163
	global_store_dwordx4 v193, v[160:163], s[42:43]
	s_waitcnt vmcnt(7)
; __device__ __forceinline__ unsigned pk2_(float lo, float hi) { f32x2_t v = {lo, hi}; bf16x2_t b = __builtin_convertvector(v, bf16x2_t); return __builtin_bit_cast(unsigned, b); }
;     __device__ __forceinline__ void operator()(const f32x4 (&acc)[2][2][4][2], const Unit& u, int wr, int wc, int fr, int fq) const {
;         typedef unsigned u32x2_ __attribute__((ext_vector_type(2)));
;         const int col0 = u.pn * BM + wc * 32 + 4 * fq;
; #pragma unroll
;         for (int ai = 0; ai < 2; ++ai) {
;             u32x2_ v[4][2][2];
; #pragma unroll
;             for (int m = 0; m < 4; ++m) { const bf16_t* rowp = H + (size_t)(u.pm * BM + wr * 64 + fr + ai * HALF + m * 16) * 2048 + col0;
; #pragma unroll
;                 for (int bj = 0; bj < 2; ++bj)
; #pragma unroll
;                     for (int n = 0; n < 2; ++n) v[m][bj][n] = *(const u32x2_*)(rowp + bj * HALF + n * 16); }
; #pragma unroll
;             for (int m = 0; m < 4; ++m) { bf16_t* rowp = H + (size_t)(u.pm * BM + wr * 64 + fr + ai * HALF + m * 16) * 2048 + col0;
; #pragma unroll
;                 for (int bj = 0; bj < 2; ++bj)
; #pragma unroll
;                     for (int n = 0; n < 2; ++n) { const f32x4 a = acc[ai][bj][m][n]; const u32x2_ o = v[m][bj][n];
;                         u32x2_ w; w.x = pk2_(bflo(o.x) + a[0], bfhi(o.x) + a[1]); w.y = pk2_(bflo(o.y) + a[2], bfhi(o.y) + a[3]); *(u32x2_*)(rowp + bj * HALF + n * 16) = w; } }
;             asm volatile("" ::: "memory");
;         }
;     }
	v_permlane16_swap_b32_e32 v164, v166
	v_permlane16_swap_b32_e32 v165, v167
	v_lshlrev_b32_e32 v177, 16, v164
	v_and_b32_e32 v182, 0xffff0000, v164
	v_lshlrev_b32_e32 v183, 16, v165
	v_and_b32_e32 v192, 0xffff0000, v165
	v_add_f32_e32 v86, v86, v177
	v_add_f32_e32 v87, v87, v182
	v_add_f32_e32 v88, v88, v183
	v_add_f32_e32 v89, v89, v192
	v_lshlrev_b32_e32 v177, 16, v166
	v_and_b32_e32 v182, 0xffff0000, v166
	v_lshlrev_b32_e32 v183, 16, v167
	v_and_b32_e32 v192, 0xffff0000, v167
	v_add_f32_e32 v78, v78, v177
	v_add_f32_e32 v79, v79, v182
	v_add_f32_e32 v80, v80, v183
	v_add_f32_e32 v81, v81, v192
	v_cvt_pk_bf16_f32 v164, v86, v87
	v_cvt_pk_bf16_f32 v165, v88, v89
	v_cvt_pk_bf16_f32 v166, v78, v79
	v_cvt_pk_bf16_f32 v167, v80, v81
	s_nop 1
	v_permlane16_swap_b32_e32 v164, v166
	v_permlane16_swap_b32_e32 v165, v167
	global_store_dwordx4 v193, v[164:167], s[42:43] offset:256
	v_add_u32_e32 v193, 0x10000, v193
	s_waitcnt vmcnt(7)
	v_permlane16_swap_b32_e32 v168, v170
	v_permlane16_swap_b32_e32 v169, v171
	v_lshlrev_b32_e32 v177, 16, v168
	v_and_b32_e32 v182, 0xffff0000, v168
	v_lshlrev_b32_e32 v183, 16, v169
	v_and_b32_e32 v192, 0xffff0000, v169
	v_add_f32_e32 v82, v82, v177
	v_add_f32_e32 v83, v83, v182
	v_add_f32_e32 v84, v84, v183
	v_add_f32_e32 v85, v85, v192
	v_lshlrev_b32_e32 v177, 16, v170
	v_and_b32_e32 v182, 0xffff0000, v170
	v_lshlrev_b32_e32 v183, 16, v171
	v_and_b32_e32 v192, 0xffff0000, v171
	v_add_f32_e32 v74, v74, v177
	v_add_f32_e32 v75, v75, v182
	v_add_f32_e32 v76, v76, v183
	v_add_f32_e32 v77, v77, v192
	v_cvt_pk_bf16_f32 v168, v82, v83
	v_cvt_pk_bf16_f32 v169, v84, v85
	v_cvt_pk_bf16_f32 v170, v74, v75
	v_cvt_pk_bf16_f32 v171, v76, v77
	s_nop 1
	v_permlane16_swap_b32_e32 v168, v170
	v_permlane16_swap_b32_e32 v169, v171
	global_store_dwordx4 v193, v[168:171], s[42:43]
	s_waitcnt vmcnt(7)
	v_permlane16_swap_b32_e32 v172, v174
	v_permlane16_swap_b32_e32 v173, v175
	v_lshlrev_b32_e32 v177, 16, v172
	v_and_b32_e32 v182, 0xffff0000, v172
	v_lshlrev_b32_e32 v183, 16, v173
	v_and_b32_e32 v192, 0xffff0000, v173
	v_add_f32_e32 v70, v70, v177
	v_add_f32_e32 v71, v71, v182
	v_add_f32_e32 v72, v72, v183
	v_add_f32_e32 v73, v73, v192
	v_lshlrev_b32_e32 v177, 16, v174
	v_and_b32_e32 v182, 0xffff0000, v174
	v_lshlrev_b32_e32 v183, 16, v175
	v_and_b32_e32 v192, 0xffff0000, v175
	v_add_f32_e32 v66, v66, v177
	v_add_f32_e32 v67, v67, v182
	v_add_f32_e32 v68, v68, v183
	v_add_f32_e32 v69, v69, v192
	v_cvt_pk_bf16_f32 v172, v70, v71
	v_cvt_pk_bf16_f32 v173, v72, v73
	v_cvt_pk_bf16_f32 v174, v66, v67
	v_cvt_pk_bf16_f32 v175, v68, v69
	s_nop 1
	v_permlane16_swap_b32_e32 v172, v174
	v_permlane16_swap_b32_e32 v173, v175
	global_store_dwordx4 v193, v[172:175], s[42:43] offset:256
	v_add_u32_e32 v193, 0x50000, v193
	global_load_dwordx4 v[144:147], v176, s[42:43]
	global_load_dwordx4 v[148:151], v176, s[42:43] offset:256
	v_add_u32_e32 v176, 0x10000, v176
	global_load_dwordx4 v[152:155], v176, s[42:43]
	global_load_dwordx4 v[156:159], v176, s[42:43] offset:256
	v_add_u32_e32 v176, 0x10000, v176
	global_load_dwordx4 v[160:163], v176, s[42:43]
	global_load_dwordx4 v[164:167], v176, s[42:43] offset:256
	v_add_u32_e32 v176, 0x10000, v176
	global_load_dwordx4 v[168:171], v176, s[42:43]
	global_load_dwordx4 v[172:175], v176, s[42:43] offset:256
	v_add_u32_e32 v176, 0x50000, v176
	s_waitcnt vmcnt(7)
	v_permlane16_swap_b32_e32 v144, v146
	v_permlane16_swap_b32_e32 v145, v147
	v_lshlrev_b32_e32 v177, 16, v144
	v_and_b32_e32 v182, 0xffff0000, v144
	v_lshlrev_b32_e32 v183, 16, v145
	v_and_b32_e32 v192, 0xffff0000, v145
	v_add_f32_e32 v62, v62, v177
	v_add_f32_e32 v63, v63, v182
	v_add_f32_e32 v64, v64, v183
	v_add_f32_e32 v65, v65, v192
	v_lshlrev_b32_e32 v177, 16, v146
	v_and_b32_e32 v182, 0xffff0000, v146
	v_lshlrev_b32_e32 v183, 16, v147
	v_and_b32_e32 v192, 0xffff0000, v147
	v_add_f32_e32 v58, v58, v177
	v_add_f32_e32 v59, v59, v182
	v_add_f32_e32 v60, v60, v183
	v_add_f32_e32 v61, v61, v192
	v_cvt_pk_bf16_f32 v144, v62, v63
	v_cvt_pk_bf16_f32 v145, v64, v65
	v_cvt_pk_bf16_f32 v146, v58, v59
	v_cvt_pk_bf16_f32 v147, v60, v61
	s_nop 1
	v_permlane16_swap_b32_e32 v144, v146
	v_permlane16_swap_b32_e32 v145, v147
	global_store_dwordx4 v193, v[144:147], s[42:43]
	s_waitcnt vmcnt(7)
	v_permlane16_swap_b32_e32 v148, v150
	v_permlane16_swap_b32_e32 v149, v151
	v_lshlrev_b32_e32 v177, 16, v148
	v_and_b32_e32 v182, 0xffff0000, v148
	v_lshlrev_b32_e32 v183, 16, v149
	v_and_b32_e32 v192, 0xffff0000, v149
	v_add_f32_e32 v54, v54, v177
	v_add_f32_e32 v55, v55, v182
	v_add_f32_e32 v56, v56, v183
	v_add_f32_e32 v57, v57, v192
	v_lshlrev_b32_e32 v177, 16, v150
	v_and_b32_e32 v182, 0xffff0000, v150
	v_lshlrev_b32_e32 v183, 16, v151
	v_and_b32_e32 v192, 0xffff0000, v151
	v_add_f32_e32 v46, v46, v177
	v_add_f32_e32 v47, v47, v182
	v_add_f32_e32 v48, v48, v183
	v_add_f32_e32 v49, v49, v192
	v_cvt_pk_bf16_f32 v148, v54, v55
	v_cvt_pk_bf16_f32 v149, v56, v57
	v_cvt_pk_bf16_f32 v150, v46, v47
	v_cvt_pk_bf16_f32 v151, v48, v49
	s_nop 1
	v_permlane16_swap_b32_e32 v148, v150
	v_permlane16_swap_b32_e32 v149, v151
	global_store_dwordx4 v193, v[148:151], s[42:43] offset:256
	v_add_u32_e32 v193, 0x10000, v193
	s_waitcnt vmcnt(7)
; __device__ __forceinline__ unsigned pk2_(float lo, float hi) { f32x2_t v = {lo, hi}; bf16x2_t b = __builtin_convertvector(v, bf16x2_t); return __builtin_bit_cast(unsigned, b); }
;     __device__ __forceinline__ void operator()(const f32x4 (&acc)[2][2][4][2], const Unit& u, int wr, int wc, int fr, int fq) const {
;         typedef unsigned u32x2_ __attribute__((ext_vector_type(2)));
;         const int col0 = u.pn * BM + wc * 32 + 4 * fq;
; #pragma unroll
;         for (int ai = 0; ai < 2; ++ai) {
;             u32x2_ v[4][2][2];
; #pragma unroll
;             for (int m = 0; m < 4; ++m) { const bf16_t* rowp = H + (size_t)(u.pm * BM + wr * 64 + fr + ai * HALF + m * 16) * 2048 + col0;
; #pragma unroll
;                 for (int bj = 0; bj < 2; ++bj)
; #pragma unroll
;                     for (int n = 0; n < 2; ++n) v[m][bj][n] = *(const u32x2_*)(rowp + bj * HALF + n * 16); }
; #pragma unroll
;             for (int m = 0; m < 4; ++m) { bf16_t* rowp = H + (size_t)(u.pm * BM + wr * 64 + fr + ai * HALF + m * 16) * 2048 + col0;
; #pragma unroll
;                 for (int bj = 0; bj < 2; ++bj)
; #pragma unroll
;                     for (int n = 0; n < 2; ++n) { const f32x4 a = acc[ai][bj][m][n]; const u32x2_ o = v[m][bj][n];
;                         u32x2_ w; w.x = pk2_(bflo(o.x) + a[0], bfhi(o.x) + a[1]); w.y = pk2_(bflo(o.y) + a[2], bfhi(o.y) + a[3]); *(u32x2_*)(rowp + bj * HALF + n * 16) = w; } }
;             asm volatile("" ::: "memory");
;         }
;     }
	v_permlane16_swap_b32_e32 v152, v154
	v_permlane16_swap_b32_e32 v153, v155
	v_lshlrev_b32_e32 v177, 16, v152
	v_and_b32_e32 v182, 0xffff0000, v152
	v_lshlrev_b32_e32 v183, 16, v153
	v_and_b32_e32 v192, 0xffff0000, v153
	v_add_f32_e32 v50, v50, v177
	v_add_f32_e32 v51, v51, v182
	v_add_f32_e32 v52, v52, v183
	v_add_f32_e32 v53, v53, v192
	v_lshlrev_b32_e32 v177, 16, v154
	v_and_b32_e32 v182, 0xffff0000, v154
	v_lshlrev_b32_e32 v183, 16, v155
	v_and_b32_e32 v192, 0xffff0000, v155
	v_add_f32_e32 v42, v42, v177
	v_add_f32_e32 v43, v43, v182
	v_add_f32_e32 v44, v44, v183
	v_add_f32_e32 v45, v45, v192
	v_cvt_pk_bf16_f32 v152, v50, v51
	v_cvt_pk_bf16_f32 v153, v52, v53
	v_cvt_pk_bf16_f32 v154, v42, v43
	v_cvt_pk_bf16_f32 v155, v44, v45
	s_nop 1
	v_permlane16_swap_b32_e32 v152, v154
	v_permlane16_swap_b32_e32 v153, v155
	global_store_dwordx4 v193, v[152:155], s[42:43]
	s_waitcnt vmcnt(7)
	v_permlane16_swap_b32_e32 v156, v158
	v_permlane16_swap_b32_e32 v157, v159
	v_lshlrev_b32_e32 v177, 16, v156
	v_and_b32_e32 v182, 0xffff0000, v156
	v_lshlrev_b32_e32 v183, 16, v157
	v_and_b32_e32 v192, 0xffff0000, v157
	v_add_f32_e32 v38, v38, v177
	v_add_f32_e32 v39, v39, v182
	v_add_f32_e32 v40, v40, v183
	v_add_f32_e32 v41, v41, v192
	v_lshlrev_b32_e32 v177, 16, v158
	v_and_b32_e32 v182, 0xffff0000, v158
	v_lshlrev_b32_e32 v183, 16, v159
	v_and_b32_e32 v192, 0xffff0000, v159
	v_add_f32_e32 v30, v30, v177
	v_add_f32_e32 v31, v31, v182
	v_add_f32_e32 v32, v32, v183
	v_add_f32_e32 v33, v33, v192
	v_cvt_pk_bf16_f32 v156, v38, v39
	v_cvt_pk_bf16_f32 v157, v40, v41
	v_cvt_pk_bf16_f32 v158, v30, v31
	v_cvt_pk_bf16_f32 v159, v32, v33
	s_nop 1
	v_permlane16_swap_b32_e32 v156, v158
	v_permlane16_swap_b32_e32 v157, v159
	global_store_dwordx4 v193, v[156:159], s[42:43] offset:256
	v_add_u32_e32 v193, 0x10000, v193
	s_waitcnt vmcnt(7)
	v_permlane16_swap_b32_e32 v160, v162
	v_permlane16_swap_b32_e32 v161, v163
	v_lshlrev_b32_e32 v177, 16, v160
	v_and_b32_e32 v182, 0xffff0000, v160
	v_lshlrev_b32_e32 v183, 16, v161
	v_and_b32_e32 v192, 0xffff0000, v161
	v_add_f32_e32 v34, v34, v177
	v_add_f32_e32 v35, v35, v182
	v_add_f32_e32 v36, v36, v183
	v_add_f32_e32 v37, v37, v192
	v_lshlrev_b32_e32 v177, 16, v162
	v_and_b32_e32 v182, 0xffff0000, v162
	v_lshlrev_b32_e32 v183, 16, v163
	v_and_b32_e32 v192, 0xffff0000, v163
	v_add_f32_e32 v26, v26, v177
	v_add_f32_e32 v27, v27, v182
	v_add_f32_e32 v28, v28, v183
	v_add_f32_e32 v29, v29, v192
	v_cvt_pk_bf16_f32 v160, v34, v35
	v_cvt_pk_bf16_f32 v161, v36, v37
	v_cvt_pk_bf16_f32 v162, v26, v27
	v_cvt_pk_bf16_f32 v163, v28, v29
	s_nop 1
	v_permlane16_swap_b32_e32 v160, v162
	v_permlane16_swap_b32_e32 v161, v163
	global_store_dwordx4 v193, v[160:163], s[42:43]
	s_waitcnt vmcnt(7)
	v_permlane16_swap_b32_e32 v164, v166
	v_permlane16_swap_b32_e32 v165, v167
	v_lshlrev_b32_e32 v177, 16, v164
	v_and_b32_e32 v182, 0xffff0000, v164
	v_lshlrev_b32_e32 v183, 16, v165
	v_and_b32_e32 v192, 0xffff0000, v165
	v_add_f32_e32 v22, v22, v177
	v_add_f32_e32 v23, v23, v182
	v_add_f32_e32 v24, v24, v183
	v_add_f32_e32 v25, v25, v192
	v_lshlrev_b32_e32 v177, 16, v166
	v_and_b32_e32 v182, 0xffff0000, v166
	v_lshlrev_b32_e32 v183, 16, v167
	v_and_b32_e32 v192, 0xffff0000, v167
	v_add_f32_e32 v12, v12, v177
	v_add_f32_e32 v13, v13, v182
	v_add_f32_e32 v14, v14, v183
	v_add_f32_e32 v15, v15, v192
	v_cvt_pk_bf16_f32 v164, v22, v23
	v_cvt_pk_bf16_f32 v165, v24, v25
	v_cvt_pk_bf16_f32 v166, v12, v13
	v_cvt_pk_bf16_f32 v167, v14, v15
	s_nop 1
	v_permlane16_swap_b32_e32 v164, v166
	v_permlane16_swap_b32_e32 v165, v167
	global_store_dwordx4 v193, v[164:167], s[42:43] offset:256
	v_add_u32_e32 v193, 0x10000, v193
	s_waitcnt vmcnt(7)
	v_permlane16_swap_b32_e32 v168, v170
	v_permlane16_swap_b32_e32 v169, v171
	v_lshlrev_b32_e32 v177, 16, v168
	v_and_b32_e32 v182, 0xffff0000, v168
	v_lshlrev_b32_e32 v183, 16, v169
	v_and_b32_e32 v192, 0xffff0000, v169
	v_add_f32_e32 v18, v18, v177
	v_add_f32_e32 v19, v19, v182
	v_add_f32_e32 v20, v20, v183
	v_add_f32_e32 v21, v21, v192
	v_lshlrev_b32_e32 v177, 16, v170
	v_and_b32_e32 v182, 0xffff0000, v170
	v_lshlrev_b32_e32 v183, 16, v171
	v_and_b32_e32 v192, 0xffff0000, v171
	v_add_f32_e32 v8, v8, v177
	v_add_f32_e32 v9, v9, v182
	v_add_f32_e32 v10, v10, v183
	v_add_f32_e32 v11, v11, v192
	v_cvt_pk_bf16_f32 v168, v18, v19
	v_cvt_pk_bf16_f32 v169, v20, v21
	v_cvt_pk_bf16_f32 v170, v8, v9
	v_cvt_pk_bf16_f32 v171, v10, v11
	s_nop 1
	v_permlane16_swap_b32_e32 v168, v170
	v_permlane16_swap_b32_e32 v169, v171
	global_store_dwordx4 v193, v[168:171], s[42:43]
	s_waitcnt vmcnt(7)
	v_permlane16_swap_b32_e32 v172, v174
	v_permlane16_swap_b32_e32 v173, v175
	v_lshlrev_b32_e32 v177, 16, v172
	v_and_b32_e32 v182, 0xffff0000, v172
	v_lshlrev_b32_e32 v183, 16, v173
	v_and_b32_e32 v192, 0xffff0000, v173
	v_add_f32_e32 v4, v4, v177
	v_add_f32_e32 v5, v5, v182
	v_add_f32_e32 v6, v6, v183
	v_add_f32_e32 v7, v7, v192
	v_lshlrev_b32_e32 v177, 16, v174
	v_and_b32_e32 v182, 0xffff0000, v174
	v_lshlrev_b32_e32 v183, 16, v175
	v_and_b32_e32 v192, 0xffff0000, v175
	v_add_f32_e32 v0, v0, v177
	v_add_f32_e32 v1, v1, v182
	v_add_f32_e32 v2, v2, v183
	v_add_f32_e32 v3, v3, v192
	v_cvt_pk_bf16_f32 v172, v4, v5
	v_cvt_pk_bf16_f32 v173, v6, v7
	v_cvt_pk_bf16_f32 v174, v0, v1
	v_cvt_pk_bf16_f32 v175, v2, v3
	s_nop 1
	v_permlane16_swap_b32_e32 v172, v174
	v_permlane16_swap_b32_e32 v173, v175
	global_store_dwordx4 v193, v[172:175], s[42:43] offset:256
	v_add_u32_e32 v193, 0x50000, v193
	s_mov_b64 s[12:13], -1
	s_and_b64 vcc, exec, s[38:39]
	s_cbranch_vccnz .LBB0_1362
	s_andn2_b64 vcc, exec, s[40:41]
	s_cbranch_vccnz .LBB0_1361
	s_barrier
	s_branch .LBB0_1361

; __device__ __forceinline__ unsigned pk2_(float lo, float hi) { f32x2_t v = {lo, hi}; bf16x2_t b = __builtin_convertvector(v, bf16x2_t); return __builtin_bit_cast(unsigned, b); }
;     __device__ __forceinline__ void operator()(const f32x4 (&acc)[2][2][4][2], const Unit& u, int wr, int wc, int fr, int fq) const {
;         typedef unsigned u32x2_ __attribute__((ext_vector_type(2)));
;         const int col0 = u.pn * BM + wc * 32 + 4 * fq;
; #pragma unroll
;         for (int ai = 0; ai < 2; ++ai) {
;             u32x2_ v[4][2][2];
; #pragma unroll
;             for (int m = 0; m < 4; ++m) { const bf16_t* rowp = H + (size_t)(u.pm * BM + wr * 64 + fr + ai * HALF + m * 16) * 2048 + col0;
; #pragma unroll
;                 for (int bj = 0; bj < 2; ++bj)
; #pragma unroll
;                     for (int n = 0; n < 2; ++n) v[m][bj][n] = *(const u32x2_*)(rowp + bj * HALF + n * 16); }
; #pragma unroll
;             for (int m = 0; m < 4; ++m) { bf16_t* rowp = H + (size_t)(u.pm * BM + wr * 64 + fr + ai * HALF + m * 16) * 2048 + col0;
; #pragma unroll
;                 for (int bj = 0; bj < 2; ++bj)
; #pragma unroll
;                     for (int n = 0; n < 2; ++n) { const f32x4 a = acc[ai][bj][m][n]; const u32x2_ o = v[m][bj][n];
;                         u32x2_ w; w.x = pk2_(bflo(o.x) + a[0], bfhi(o.x) + a[1]); w.y = pk2_(bflo(o.y) + a[2], bfhi(o.y) + a[3]); *(u32x2_*)(rowp + bj * HALF + n * 16) = w; } }
;             asm volatile("" ::: "memory");
;         }
;     }
.LBB0_1654:
	v_and_b32_e32 v138, 16, v213
	v_lshrrev_b32_e32 v138, 2, v138
	v_mul_u32_u24_e32 v138, 3, v138
	v_add_u32_e32 v139, v175, v138
	v_lshl_or_b32 v139, s30, 8, v139
	v_lshl_add_u32 v172, s29, 8, v17
	v_lshlrev_b32_e32 v172, 12, v172
	v_lshl_add_u32 v172, v139, 1, v172
	v_mov_b32_e32 v189, v172
	global_load_dwordx4 v[140:143], v172, s[74:75]
	global_load_dwordx4 v[144:147], v172, s[74:75] offset:256
	v_add_u32_e32 v172, 0x10000, v172
	global_load_dwordx4 v[148:151], v172, s[74:75]
	global_load_dwordx4 v[152:155], v172, s[74:75] offset:256
	v_add_u32_e32 v172, 0x10000, v172
	global_load_dwordx4 v[156:159], v172, s[74:75]
	global_load_dwordx4 v[160:163], v172, s[74:75] offset:256
	v_add_u32_e32 v172, 0x10000, v172
	global_load_dwordx4 v[164:167], v172, s[74:75]
	global_load_dwordx4 v[168:171], v172, s[74:75] offset:256
	v_add_u32_e32 v172, 0x50000, v172
	s_waitcnt vmcnt(7)
	v_permlane16_swap_b32_e32 v140, v142
	v_permlane16_swap_b32_e32 v141, v143
	v_lshlrev_b32_e32 v173, 16, v140
	v_and_b32_e32 v178, 0xffff0000, v140
	v_lshlrev_b32_e32 v179, 16, v141
	v_and_b32_e32 v188, 0xffff0000, v141
	v_add_f32_e32 v126, v126, v173
	v_add_f32_e32 v127, v127, v178
	v_add_f32_e32 v128, v128, v179
	v_add_f32_e32 v129, v129, v188
	v_lshlrev_b32_e32 v173, 16, v142
	v_and_b32_e32 v178, 0xffff0000, v142
	v_lshlrev_b32_e32 v179, 16, v143
	v_and_b32_e32 v188, 0xffff0000, v143
	v_add_f32_e32 v122, v122, v173
	v_add_f32_e32 v123, v123, v178
	v_add_f32_e32 v124, v124, v179
	v_add_f32_e32 v125, v125, v188
	v_cvt_pk_bf16_f32 v140, v126, v127
	v_cvt_pk_bf16_f32 v141, v128, v129
	v_cvt_pk_bf16_f32 v142, v122, v123
	v_cvt_pk_bf16_f32 v143, v124, v125
	s_nop 1
	v_permlane16_swap_b32_e32 v140, v142
	v_permlane16_swap_b32_e32 v141, v143
	global_store_dwordx4 v189, v[140:143], s[74:75]
	s_waitcnt vmcnt(7)
	v_permlane16_swap_b32_e32 v144, v146
	v_permlane16_swap_b32_e32 v145, v147
	v_lshlrev_b32_e32 v173, 16, v144
	v_and_b32_e32 v178, 0xffff0000, v144
	v_lshlrev_b32_e32 v179, 16, v145
	v_and_b32_e32 v188, 0xffff0000, v145
	v_add_f32_e32 v118, v118, v173
	v_add_f32_e32 v119, v119, v178
	v_add_f32_e32 v120, v120, v179
	v_add_f32_e32 v121, v121, v188
	v_lshlrev_b32_e32 v173, 16, v146
	v_and_b32_e32 v178, 0xffff0000, v146
	v_lshlrev_b32_e32 v179, 16, v147
	v_and_b32_e32 v188, 0xffff0000, v147
	v_add_f32_e32 v114, v114, v173
	v_add_f32_e32 v115, v115, v178
	v_add_f32_e32 v116, v116, v179
	v_add_f32_e32 v117, v117, v188
	v_cvt_pk_bf16_f32 v144, v118, v119
	v_cvt_pk_bf16_f32 v145, v120, v121
	v_cvt_pk_bf16_f32 v146, v114, v115
	v_cvt_pk_bf16_f32 v147, v116, v117
	s_nop 1
	v_permlane16_swap_b32_e32 v144, v146
	v_permlane16_swap_b32_e32 v145, v147
	global_store_dwordx4 v189, v[144:147], s[74:75] offset:256
	v_add_u32_e32 v189, 0x10000, v189
	s_waitcnt vmcnt(7)
	v_permlane16_swap_b32_e32 v148, v150
	v_permlane16_swap_b32_e32 v149, v151
	v_lshlrev_b32_e32 v173, 16, v148
	v_and_b32_e32 v178, 0xffff0000, v148
	v_lshlrev_b32_e32 v179, 16, v149
	v_and_b32_e32 v188, 0xffff0000, v149
	v_add_f32_e32 v110, v110, v173
	v_add_f32_e32 v111, v111, v178
	v_add_f32_e32 v112, v112, v179
	v_add_f32_e32 v113, v113, v188
	v_lshlrev_b32_e32 v173, 16, v150
	v_and_b32_e32 v178, 0xffff0000, v150
	v_lshlrev_b32_e32 v179, 16, v151
	v_and_b32_e32 v188, 0xffff0000, v151
	v_add_f32_e32 v106, v106, v173
	v_add_f32_e32 v107, v107, v178
	v_add_f32_e32 v108, v108, v179
	v_add_f32_e32 v109, v109, v188
	v_cvt_pk_bf16_f32 v148, v110, v111
	v_cvt_pk_bf16_f32 v149, v112, v113
	v_cvt_pk_bf16_f32 v150, v106, v107
	v_cvt_pk_bf16_f32 v151, v108, v109
	s_nop 1
	v_permlane16_swap_b32_e32 v148, v150
	v_permlane16_swap_b32_e32 v149, v151
	global_store_dwordx4 v189, v[148:151], s[74:75]
	s_waitcnt vmcnt(7)
	v_permlane16_swap_b32_e32 v152, v154
	v_permlane16_swap_b32_e32 v153, v155
	v_lshlrev_b32_e32 v173, 16, v152
	v_and_b32_e32 v178, 0xffff0000, v152
	v_lshlrev_b32_e32 v179, 16, v153
	v_and_b32_e32 v188, 0xffff0000, v153
	v_add_f32_e32 v102, v102, v173
	v_add_f32_e32 v103, v103, v178
	v_add_f32_e32 v104, v104, v179
	v_add_f32_e32 v105, v105, v188
	v_lshlrev_b32_e32 v173, 16, v154
	v_and_b32_e32 v178, 0xffff0000, v154
	v_lshlrev_b32_e32 v179, 16, v155
	v_and_b32_e32 v188, 0xffff0000, v155
	v_add_f32_e32 v94, v94, v173
	v_add_f32_e32 v95, v95, v178
	v_add_f32_e32 v96, v96, v179
	v_add_f32_e32 v97, v97, v188
	v_cvt_pk_bf16_f32 v152, v102, v103
	v_cvt_pk_bf16_f32 v153, v104, v105
	v_cvt_pk_bf16_f32 v154, v94, v95
	v_cvt_pk_bf16_f32 v155, v96, v97
	s_nop 1
	v_permlane16_swap_b32_e32 v152, v154
	v_permlane16_swap_b32_e32 v153, v155
	global_store_dwordx4 v189, v[152:155], s[74:75] offset:256
	v_add_u32_e32 v189, 0x10000, v189
	s_waitcnt vmcnt(7)
	v_permlane16_swap_b32_e32 v156, v158
	v_permlane16_swap_b32_e32 v157, v159
	v_lshlrev_b32_e32 v173, 16, v156
	v_and_b32_e32 v178, 0xffff0000, v156
	v_lshlrev_b32_e32 v179, 16, v157
	v_and_b32_e32 v188, 0xffff0000, v157
	v_add_f32_e32 v98, v98, v173
	v_add_f32_e32 v99, v99, v178
	v_add_f32_e32 v100, v100, v179
	v_add_f32_e32 v101, v101, v188
	v_lshlrev_b32_e32 v173, 16, v158
	v_and_b32_e32 v178, 0xffff0000, v158
	v_lshlrev_b32_e32 v179, 16, v159
	v_and_b32_e32 v188, 0xffff0000, v159
	v_add_f32_e32 v90, v90, v173
	v_add_f32_e32 v91, v91, v178
	v_add_f32_e32 v92, v92, v179
	v_add_f32_e32 v93, v93, v188
	v_cvt_pk_bf16_f32 v156, v98, v99
	v_cvt_pk_bf16_f32 v157, v100, v101
	v_cvt_pk_bf16_f32 v158, v90, v91
	v_cvt_pk_bf16_f32 v159, v92, v93
	s_nop 1
	v_permlane16_swap_b32_e32 v156, v158
	v_permlane16_swap_b32_e32 v157, v159
	global_store_dwordx4 v189, v[156:159], s[74:75]
	s_waitcnt vmcnt(7)
; __device__ __forceinline__ unsigned pk2_(float lo, float hi) { f32x2_t v = {lo, hi}; bf16x2_t b = __builtin_convertvector(v, bf16x2_t); return __builtin_bit_cast(unsigned, b); }
;     __device__ __forceinline__ void operator()(const f32x4 (&acc)[2][2][4][2], const Unit& u, int wr, int wc, int fr, int fq) const {
;         typedef unsigned u32x2_ __attribute__((ext_vector_type(2)));
;         const int col0 = u.pn * BM + wc * 32 + 4 * fq;
; #pragma unroll
;         for (int ai = 0; ai < 2; ++ai) {
;             u32x2_ v[4][2][2];
; #pragma unroll
;             for (int m = 0; m < 4; ++m) { const bf16_t* rowp = H + (size_t)(u.pm * BM + wr * 64 + fr + ai * HALF + m * 16) * 2048 + col0;
; #pragma unroll
;                 for (int bj = 0; bj < 2; ++bj)
; #pragma unroll
;                     for (int n = 0; n < 2; ++n) v[m][bj][n] = *(const u32x2_*)(rowp + bj * HALF + n * 16); }
; #pragma unroll
;             for (int m = 0; m < 4; ++m) { bf16_t* rowp = H + (size_t)(u.pm * BM + wr * 64 + fr + ai * HALF + m * 16) * 2048 + col0;
; #pragma unroll
;                 for (int bj = 0; bj < 2; ++bj)
; #pragma unroll
;                     for (int n = 0; n < 2; ++n) { const f32x4 a = acc[ai][bj][m][n]; const u32x2_ o = v[m][bj][n];
;                         u32x2_ w; w.x = pk2_(bflo(o.x) + a[0], bfhi(o.x) + a[1]); w.y = pk2_(bflo(o.y) + a[2], bfhi(o.y) + a[3]); *(u32x2_*)(rowp + bj * HALF + n * 16) = w; } }
;             asm volatile("" ::: "memory");
;         }
;     }
	v_permlane16_swap_b32_e32 v160, v162
	v_permlane16_swap_b32_e32 v161, v163
	v_lshlrev_b32_e32 v173, 16, v160
	v_and_b32_e32 v178, 0xffff0000, v160
	v_lshlrev_b32_e32 v179, 16, v161
	v_and_b32_e32 v188, 0xffff0000, v161
	v_add_f32_e32 v86, v86, v173
	v_add_f32_e32 v87, v87, v178
	v_add_f32_e32 v88, v88, v179
	v_add_f32_e32 v89, v89, v188
	v_lshlrev_b32_e32 v173, 16, v162
	v_and_b32_e32 v178, 0xffff0000, v162
	v_lshlrev_b32_e32 v179, 16, v163
	v_and_b32_e32 v188, 0xffff0000, v163
	v_add_f32_e32 v78, v78, v173
	v_add_f32_e32 v79, v79, v178
	v_add_f32_e32 v80, v80, v179
	v_add_f32_e32 v81, v81, v188
	v_cvt_pk_bf16_f32 v160, v86, v87
	v_cvt_pk_bf16_f32 v161, v88, v89
	v_cvt_pk_bf16_f32 v162, v78, v79
	v_cvt_pk_bf16_f32 v163, v80, v81
	s_nop 1
	v_permlane16_swap_b32_e32 v160, v162
	v_permlane16_swap_b32_e32 v161, v163
	global_store_dwordx4 v189, v[160:163], s[74:75] offset:256
	v_add_u32_e32 v189, 0x10000, v189
	s_waitcnt vmcnt(7)
	v_permlane16_swap_b32_e32 v164, v166
	v_permlane16_swap_b32_e32 v165, v167
	v_lshlrev_b32_e32 v173, 16, v164
	v_and_b32_e32 v178, 0xffff0000, v164
	v_lshlrev_b32_e32 v179, 16, v165
	v_and_b32_e32 v188, 0xffff0000, v165
	v_add_f32_e32 v82, v82, v173
	v_add_f32_e32 v83, v83, v178
	v_add_f32_e32 v84, v84, v179
	v_add_f32_e32 v85, v85, v188
	v_lshlrev_b32_e32 v173, 16, v166
	v_and_b32_e32 v178, 0xffff0000, v166
	v_lshlrev_b32_e32 v179, 16, v167
	v_and_b32_e32 v188, 0xffff0000, v167
	v_add_f32_e32 v74, v74, v173
	v_add_f32_e32 v75, v75, v178
	v_add_f32_e32 v76, v76, v179
	v_add_f32_e32 v77, v77, v188
	v_cvt_pk_bf16_f32 v164, v82, v83
	v_cvt_pk_bf16_f32 v165, v84, v85
	v_cvt_pk_bf16_f32 v166, v74, v75
	v_cvt_pk_bf16_f32 v167, v76, v77
	s_nop 1
	v_permlane16_swap_b32_e32 v164, v166
	v_permlane16_swap_b32_e32 v165, v167
	global_store_dwordx4 v189, v[164:167], s[74:75]
	s_waitcnt vmcnt(7)
	v_permlane16_swap_b32_e32 v168, v170
	v_permlane16_swap_b32_e32 v169, v171
	v_lshlrev_b32_e32 v173, 16, v168
	v_and_b32_e32 v178, 0xffff0000, v168
	v_lshlrev_b32_e32 v179, 16, v169
	v_and_b32_e32 v188, 0xffff0000, v169
	v_add_f32_e32 v70, v70, v173
	v_add_f32_e32 v71, v71, v178
	v_add_f32_e32 v72, v72, v179
	v_add_f32_e32 v73, v73, v188
	v_lshlrev_b32_e32 v173, 16, v170
	v_and_b32_e32 v178, 0xffff0000, v170
	v_lshlrev_b32_e32 v179, 16, v171
	v_and_b32_e32 v188, 0xffff0000, v171
	v_add_f32_e32 v66, v66, v173
	v_add_f32_e32 v67, v67, v178
	v_add_f32_e32 v68, v68, v179
	v_add_f32_e32 v69, v69, v188
	v_cvt_pk_bf16_f32 v168, v70, v71
	v_cvt_pk_bf16_f32 v169, v72, v73
	v_cvt_pk_bf16_f32 v170, v66, v67
	v_cvt_pk_bf16_f32 v171, v68, v69
	s_nop 1
	v_permlane16_swap_b32_e32 v168, v170
	v_permlane16_swap_b32_e32 v169, v171
	global_store_dwordx4 v189, v[168:171], s[74:75] offset:256
	v_add_u32_e32 v189, 0x50000, v189
	global_load_dwordx4 v[140:143], v172, s[74:75]
	global_load_dwordx4 v[144:147], v172, s[74:75] offset:256
	v_add_u32_e32 v172, 0x10000, v172
	global_load_dwordx4 v[148:151], v172, s[74:75]
	global_load_dwordx4 v[152:155], v172, s[74:75] offset:256
	v_add_u32_e32 v172, 0x10000, v172
	global_load_dwordx4 v[156:159], v172, s[74:75]
	global_load_dwordx4 v[160:163], v172, s[74:75] offset:256
	v_add_u32_e32 v172, 0x10000, v172
	global_load_dwordx4 v[164:167], v172, s[74:75]
	global_load_dwordx4 v[168:171], v172, s[74:75] offset:256
	v_add_u32_e32 v172, 0x50000, v172
	s_waitcnt vmcnt(7)
	v_permlane16_swap_b32_e32 v140, v142
	v_permlane16_swap_b32_e32 v141, v143
	v_lshlrev_b32_e32 v173, 16, v140
	v_and_b32_e32 v178, 0xffff0000, v140
	v_lshlrev_b32_e32 v179, 16, v141
	v_and_b32_e32 v188, 0xffff0000, v141
	v_add_f32_e32 v62, v62, v173
	v_add_f32_e32 v63, v63, v178
	v_add_f32_e32 v64, v64, v179
	v_add_f32_e32 v65, v65, v188
	v_lshlrev_b32_e32 v173, 16, v142
	v_and_b32_e32 v178, 0xffff0000, v142
	v_lshlrev_b32_e32 v179, 16, v143
	v_and_b32_e32 v188, 0xffff0000, v143
	v_add_f32_e32 v58, v58, v173
	v_add_f32_e32 v59, v59, v178
	v_add_f32_e32 v60, v60, v179
	v_add_f32_e32 v61, v61, v188
	v_cvt_pk_bf16_f32 v140, v62, v63
	v_cvt_pk_bf16_f32 v141, v64, v65
	v_cvt_pk_bf16_f32 v142, v58, v59
	v_cvt_pk_bf16_f32 v143, v60, v61
	s_nop 1
	v_permlane16_swap_b32_e32 v140, v142
	v_permlane16_swap_b32_e32 v141, v143
	global_store_dwordx4 v189, v[140:143], s[74:75]
	s_waitcnt vmcnt(7)
	v_permlane16_swap_b32_e32 v144, v146
	v_permlane16_swap_b32_e32 v145, v147
	v_lshlrev_b32_e32 v173, 16, v144
	v_and_b32_e32 v178, 0xffff0000, v144
	v_lshlrev_b32_e32 v179, 16, v145
	v_and_b32_e32 v188, 0xffff0000, v145
	v_add_f32_e32 v54, v54, v173
	v_add_f32_e32 v55, v55, v178
	v_add_f32_e32 v56, v56, v179
	v_add_f32_e32 v57, v57, v188
	v_lshlrev_b32_e32 v173, 16, v146
	v_and_b32_e32 v178, 0xffff0000, v146
	v_lshlrev_b32_e32 v179, 16, v147
	v_and_b32_e32 v188, 0xffff0000, v147
	v_add_f32_e32 v46, v46, v173
	v_add_f32_e32 v47, v47, v178
	v_add_f32_e32 v48, v48, v179
	v_add_f32_e32 v49, v49, v188
	v_cvt_pk_bf16_f32 v144, v54, v55
	v_cvt_pk_bf16_f32 v145, v56, v57
	v_cvt_pk_bf16_f32 v146, v46, v47
	v_cvt_pk_bf16_f32 v147, v48, v49
	s_nop 1
	v_permlane16_swap_b32_e32 v144, v146
	v_permlane16_swap_b32_e32 v145, v147
	global_store_dwordx4 v189, v[144:147], s[74:75] offset:256
	v_add_u32_e32 v189, 0x10000, v189
	s_waitcnt vmcnt(7)
; __device__ __forceinline__ unsigned pk2_(float lo, float hi) { f32x2_t v = {lo, hi}; bf16x2_t b = __builtin_convertvector(v, bf16x2_t); return __builtin_bit_cast(unsigned, b); }
;     __device__ __forceinline__ void operator()(const f32x4 (&acc)[2][2][4][2], const Unit& u, int wr, int wc, int fr, int fq) const {
;         typedef unsigned u32x2_ __attribute__((ext_vector_type(2)));
;         const int col0 = u.pn * BM + wc * 32 + 4 * fq;
; #pragma unroll
;         for (int ai = 0; ai < 2; ++ai) {
;             u32x2_ v[4][2][2];
; #pragma unroll
;             for (int m = 0; m < 4; ++m) { const bf16_t* rowp = H + (size_t)(u.pm * BM + wr * 64 + fr + ai * HALF + m * 16) * 2048 + col0;
; #pragma unroll
;                 for (int bj = 0; bj < 2; ++bj)
; #pragma unroll
;                     for (int n = 0; n < 2; ++n) v[m][bj][n] = *(const u32x2_*)(rowp + bj * HALF + n * 16); }
; #pragma unroll
;             for (int m = 0; m < 4; ++m) { bf16_t* rowp = H + (size_t)(u.pm * BM + wr * 64 + fr + ai * HALF + m * 16) * 2048 + col0;
; #pragma unroll
;                 for (int bj = 0; bj < 2; ++bj)
; #pragma unroll
;                     for (int n = 0; n < 2; ++n) { const f32x4 a = acc[ai][bj][m][n]; const u32x2_ o = v[m][bj][n];
;                         u32x2_ w; w.x = pk2_(bflo(o.x) + a[0], bfhi(o.x) + a[1]); w.y = pk2_(bflo(o.y) + a[2], bfhi(o.y) + a[3]); *(u32x2_*)(rowp + bj * HALF + n * 16) = w; } }
;             asm volatile("" ::: "memory");
;         }
;     }
	v_permlane16_swap_b32_e32 v148, v150
	v_permlane16_swap_b32_e32 v149, v151
	v_lshlrev_b32_e32 v173, 16, v148
	v_and_b32_e32 v178, 0xffff0000, v148
	v_lshlrev_b32_e32 v179, 16, v149
	v_and_b32_e32 v188, 0xffff0000, v149
	v_add_f32_e32 v50, v50, v173
	v_add_f32_e32 v51, v51, v178
	v_add_f32_e32 v52, v52, v179
	v_add_f32_e32 v53, v53, v188
	v_lshlrev_b32_e32 v173, 16, v150
	v_and_b32_e32 v178, 0xffff0000, v150
	v_lshlrev_b32_e32 v179, 16, v151
	v_and_b32_e32 v188, 0xffff0000, v151
	v_add_f32_e32 v42, v42, v173
	v_add_f32_e32 v43, v43, v178
	v_add_f32_e32 v44, v44, v179
	v_add_f32_e32 v45, v45, v188
	v_cvt_pk_bf16_f32 v148, v50, v51
	v_cvt_pk_bf16_f32 v149, v52, v53
	v_cvt_pk_bf16_f32 v150, v42, v43
	v_cvt_pk_bf16_f32 v151, v44, v45
	s_nop 1
	v_permlane16_swap_b32_e32 v148, v150
	v_permlane16_swap_b32_e32 v149, v151
	global_store_dwordx4 v189, v[148:151], s[74:75]
	s_waitcnt vmcnt(7)
	v_permlane16_swap_b32_e32 v152, v154
	v_permlane16_swap_b32_e32 v153, v155
	v_lshlrev_b32_e32 v173, 16, v152
	v_and_b32_e32 v178, 0xffff0000, v152
	v_lshlrev_b32_e32 v179, 16, v153
	v_and_b32_e32 v188, 0xffff0000, v153
	v_add_f32_e32 v38, v38, v173
	v_add_f32_e32 v39, v39, v178
	v_add_f32_e32 v40, v40, v179
	v_add_f32_e32 v41, v41, v188
	v_lshlrev_b32_e32 v173, 16, v154
	v_and_b32_e32 v178, 0xffff0000, v154
	v_lshlrev_b32_e32 v179, 16, v155
	v_and_b32_e32 v188, 0xffff0000, v155
	v_add_f32_e32 v30, v30, v173
	v_add_f32_e32 v31, v31, v178
	v_add_f32_e32 v32, v32, v179
	v_add_f32_e32 v33, v33, v188
	v_cvt_pk_bf16_f32 v152, v38, v39
	v_cvt_pk_bf16_f32 v153, v40, v41
	v_cvt_pk_bf16_f32 v154, v30, v31
	v_cvt_pk_bf16_f32 v155, v32, v33
	s_nop 1
	v_permlane16_swap_b32_e32 v152, v154
	v_permlane16_swap_b32_e32 v153, v155
	global_store_dwordx4 v189, v[152:155], s[74:75] offset:256
	v_add_u32_e32 v189, 0x10000, v189
	s_waitcnt vmcnt(7)
	v_permlane16_swap_b32_e32 v156, v158
	v_permlane16_swap_b32_e32 v157, v159
	v_lshlrev_b32_e32 v173, 16, v156
	v_and_b32_e32 v178, 0xffff0000, v156
	v_lshlrev_b32_e32 v179, 16, v157
	v_and_b32_e32 v188, 0xffff0000, v157
	v_add_f32_e32 v34, v34, v173
	v_add_f32_e32 v35, v35, v178
	v_add_f32_e32 v36, v36, v179
	v_add_f32_e32 v37, v37, v188
	v_lshlrev_b32_e32 v173, 16, v158
	v_and_b32_e32 v178, 0xffff0000, v158
	v_lshlrev_b32_e32 v179, 16, v159
	v_and_b32_e32 v188, 0xffff0000, v159
	v_add_f32_e32 v26, v26, v173
	v_add_f32_e32 v27, v27, v178
	v_add_f32_e32 v28, v28, v179
	v_add_f32_e32 v29, v29, v188
	v_cvt_pk_bf16_f32 v156, v34, v35
	v_cvt_pk_bf16_f32 v157, v36, v37
	v_cvt_pk_bf16_f32 v158, v26, v27
	v_cvt_pk_bf16_f32 v159, v28, v29
	s_nop 1
	v_permlane16_swap_b32_e32 v156, v158
	v_permlane16_swap_b32_e32 v157, v159
	global_store_dwordx4 v189, v[156:159], s[74:75]
	s_waitcnt vmcnt(7)
	v_permlane16_swap_b32_e32 v160, v162
	v_permlane16_swap_b32_e32 v161, v163
	v_lshlrev_b32_e32 v173, 16, v160
	v_and_b32_e32 v178, 0xffff0000, v160
	v_lshlrev_b32_e32 v179, 16, v161
	v_and_b32_e32 v188, 0xffff0000, v161
	v_add_f32_e32 v22, v22, v173
	v_add_f32_e32 v23, v23, v178
	v_add_f32_e32 v24, v24, v179
	v_add_f32_e32 v25, v25, v188
	v_lshlrev_b32_e32 v173, 16, v162
	v_and_b32_e32 v178, 0xffff0000, v162
	v_lshlrev_b32_e32 v179, 16, v163
	v_and_b32_e32 v188, 0xffff0000, v163
	v_add_f32_e32 v12, v12, v173
	v_add_f32_e32 v13, v13, v178
	v_add_f32_e32 v14, v14, v179
	v_add_f32_e32 v15, v15, v188
	v_cvt_pk_bf16_f32 v160, v22, v23
	v_cvt_pk_bf16_f32 v161, v24, v25
	v_cvt_pk_bf16_f32 v162, v12, v13
	v_cvt_pk_bf16_f32 v163, v14, v15
	s_nop 1
	v_permlane16_swap_b32_e32 v160, v162
	v_permlane16_swap_b32_e32 v161, v163
	global_store_dwordx4 v189, v[160:163], s[74:75] offset:256
	v_add_u32_e32 v189, 0x10000, v189
	s_waitcnt vmcnt(7)
	v_permlane16_swap_b32_e32 v164, v166
	v_permlane16_swap_b32_e32 v165, v167
	v_lshlrev_b32_e32 v173, 16, v164
	v_and_b32_e32 v178, 0xffff0000, v164
	v_lshlrev_b32_e32 v179, 16, v165
	v_and_b32_e32 v188, 0xffff0000, v165
	v_add_f32_e32 v18, v18, v173
	v_add_f32_e32 v19, v19, v178
	v_add_f32_e32 v20, v20, v179
	v_add_f32_e32 v21, v21, v188
	v_lshlrev_b32_e32 v173, 16, v166
	v_and_b32_e32 v178, 0xffff0000, v166
	v_lshlrev_b32_e32 v179, 16, v167
	v_and_b32_e32 v188, 0xffff0000, v167
	v_add_f32_e32 v8, v8, v173
	v_add_f32_e32 v9, v9, v178
	v_add_f32_e32 v10, v10, v179
	v_add_f32_e32 v11, v11, v188
	v_cvt_pk_bf16_f32 v164, v18, v19
	v_cvt_pk_bf16_f32 v165, v20, v21
	v_cvt_pk_bf16_f32 v166, v8, v9
	v_cvt_pk_bf16_f32 v167, v10, v11
	s_nop 1
	v_permlane16_swap_b32_e32 v164, v166
	v_permlane16_swap_b32_e32 v165, v167
	global_store_dwordx4 v189, v[164:167], s[74:75]
	s_waitcnt vmcnt(7)
	v_permlane16_swap_b32_e32 v168, v170
	v_permlane16_swap_b32_e32 v169, v171
	v_lshlrev_b32_e32 v173, 16, v168
	v_and_b32_e32 v178, 0xffff0000, v168
	v_lshlrev_b32_e32 v179, 16, v169
	v_and_b32_e32 v188, 0xffff0000, v169
	v_add_f32_e32 v4, v4, v173
	v_add_f32_e32 v5, v5, v178
	v_add_f32_e32 v6, v6, v179
	v_add_f32_e32 v7, v7, v188
	v_lshlrev_b32_e32 v173, 16, v170
	v_and_b32_e32 v178, 0xffff0000, v170
	v_lshlrev_b32_e32 v179, 16, v171
	v_and_b32_e32 v188, 0xffff0000, v171
	v_add_f32_e32 v0, v0, v173
	v_add_f32_e32 v1, v1, v178
	v_add_f32_e32 v2, v2, v179
	v_add_f32_e32 v3, v3, v188
	v_cvt_pk_bf16_f32 v168, v4, v5
	v_cvt_pk_bf16_f32 v169, v6, v7
	v_cvt_pk_bf16_f32 v170, v0, v1
	v_cvt_pk_bf16_f32 v171, v2, v3
	s_nop 1
	v_permlane16_swap_b32_e32 v168, v170
	v_permlane16_swap_b32_e32 v169, v171
	global_store_dwordx4 v189, v[168:171], s[74:75] offset:256
	v_add_u32_e32 v189, 0x50000, v189
	s_mov_b64 s[10:11], -1
	s_and_b64 vcc, exec, s[38:39]
	s_cbranch_vccnz .LBB0_1639
	s_andn2_b64 vcc, exec, s[44:45]
	s_cbranch_vccnz .LBB0_1638
	s_barrier
	s_branch .LBB0_1638
